# hot loop heads (GEMM K loops, walk step loops, conv column loop) aligned to 64 bytes
# speedup vs baseline: 1.0077x; 1.0077x over previous
.LBB0_114:
	s_add_u32 s42, s14, 0x100
	v_mov_b32_e32 v2, 0
	s_addc_u32 s43, s15, 0
	s_mov_b32 s44, -2
	v_mov_b32_e32 v3, v2
	v_mov_b32_e32 v4, v2
	v_mov_b32_e32 v5, v2
	v_mov_b32_e32 v6, v2
	v_mov_b32_e32 v7, v2
	v_mov_b32_e32 v8, v2
	v_mov_b32_e32 v9, v2
	v_mov_b32_e32 v10, v2
	v_mov_b32_e32 v11, v2
	v_mov_b32_e32 v12, v2
	v_mov_b32_e32 v13, v2
	v_mov_b32_e32 v14, v2
	v_mov_b32_e32 v15, v2
	v_mov_b32_e32 v16, v2
	v_mov_b32_e32 v17, v2
	v_mov_b32_e32 v26, v2
	v_mov_b32_e32 v27, v2
	v_mov_b32_e32 v28, v2
	v_mov_b32_e32 v29, v2
	v_mov_b32_e32 v30, v2
	v_mov_b32_e32 v31, v2
	v_mov_b32_e32 v32, v2
	v_mov_b32_e32 v33, v2
	v_mov_b32_e32 v42, v2
	v_mov_b32_e32 v43, v2
	v_mov_b32_e32 v44, v2
	v_mov_b32_e32 v45, v2
	v_mov_b32_e32 v46, v2
	v_mov_b32_e32 v47, v2
	v_mov_b32_e32 v48, v2
	v_mov_b32_e32 v49, v2
	v_mov_b32_e32 v18, v2
	v_mov_b32_e32 v19, v2
	v_mov_b32_e32 v20, v2
	v_mov_b32_e32 v21, v2
	v_mov_b32_e32 v22, v2
	v_mov_b32_e32 v23, v2
	v_mov_b32_e32 v24, v2
	v_mov_b32_e32 v25, v2
	v_mov_b32_e32 v34, v2
	v_mov_b32_e32 v35, v2
	v_mov_b32_e32 v36, v2
	v_mov_b32_e32 v37, v2
	v_mov_b32_e32 v38, v2
	v_mov_b32_e32 v39, v2
	v_mov_b32_e32 v40, v2
	v_mov_b32_e32 v41, v2
	v_mov_b32_e32 v50, v2
	v_mov_b32_e32 v51, v2
	v_mov_b32_e32 v52, v2
	v_mov_b32_e32 v53, v2
	v_mov_b32_e32 v54, v2
	v_mov_b32_e32 v55, v2
	v_mov_b32_e32 v56, v2
	v_mov_b32_e32 v57, v2
	v_mov_b32_e32 v58, v2
	v_mov_b32_e32 v59, v2
	v_mov_b32_e32 v60, v2
	v_mov_b32_e32 v61, v2
	v_mov_b32_e32 v62, v2
	v_mov_b32_e32 v63, v2
	v_mov_b32_e32 v64, v2
	v_mov_b32_e32 v65, v2
	v_mov_b32_e32 v66, v2
	v_mov_b32_e32 v67, v2
	v_mov_b32_e32 v68, v2
	v_mov_b32_e32 v69, v2
	v_mov_b32_e32 v70, v2
	v_mov_b32_e32 v71, v2
	v_mov_b32_e32 v72, v2
	v_mov_b32_e32 v73, v2
	v_mov_b32_e32 v74, v2
	v_mov_b32_e32 v75, v2
	v_mov_b32_e32 v76, v2
	v_mov_b32_e32 v77, v2
	v_mov_b32_e32 v78, v2
	v_mov_b32_e32 v79, v2
	v_mov_b32_e32 v80, v2
	v_mov_b32_e32 v81, v2
	v_mov_b32_e32 v90, v2
	v_mov_b32_e32 v91, v2
	v_mov_b32_e32 v92, v2
	v_mov_b32_e32 v93, v2
	v_mov_b32_e32 v94, v2
	v_mov_b32_e32 v95, v2
	v_mov_b32_e32 v96, v2
	v_mov_b32_e32 v97, v2
	v_mov_b32_e32 v106, v2
	v_mov_b32_e32 v107, v2
	v_mov_b32_e32 v108, v2
	v_mov_b32_e32 v109, v2
	v_mov_b32_e32 v110, v2
	v_mov_b32_e32 v111, v2
	v_mov_b32_e32 v112, v2
	v_mov_b32_e32 v113, v2
	v_mov_b32_e32 v82, v2
	v_mov_b32_e32 v83, v2
	v_mov_b32_e32 v84, v2
	v_mov_b32_e32 v85, v2
	v_mov_b32_e32 v86, v2
	v_mov_b32_e32 v87, v2
	v_mov_b32_e32 v88, v2
	v_mov_b32_e32 v89, v2
	v_mov_b32_e32 v98, v2
	v_mov_b32_e32 v99, v2
	v_mov_b32_e32 v100, v2
	v_mov_b32_e32 v101, v2
	v_mov_b32_e32 v102, v2
	v_mov_b32_e32 v103, v2
	v_mov_b32_e32 v104, v2
	v_mov_b32_e32 v105, v2
	v_mov_b32_e32 v114, v2
	v_mov_b32_e32 v115, v2
	v_mov_b32_e32 v116, v2
	v_mov_b32_e32 v117, v2
	v_mov_b32_e32 v118, v2
	v_mov_b32_e32 v119, v2
	v_mov_b32_e32 v120, v2
	v_mov_b32_e32 v121, v2
	v_mov_b32_e32 v122, v2
	v_mov_b32_e32 v123, v2
	v_mov_b32_e32 v124, v2
	v_mov_b32_e32 v125, v2
	v_mov_b32_e32 v126, v2
	v_mov_b32_e32 v127, v2
	v_mov_b32_e32 v128, v2
	v_mov_b32_e32 v129, v2
	.p2align 6

.LBB0_152:
	s_or_b64 exec, exec, s[34:35]
	v_lshl_add_u64 v[2:3], v[90:91], 1, s[18:19]
	v_lshl_add_u64 v[142:143], v[88:89], 1, v[2:3]
	global_load_dwordx4 v[128:131], v[142:143], off
	v_add_u32_e32 v234, 2, v116
	s_mov_b64 s[34:35], 0
	s_waitcnt vmcnt(0)
	.p2align 6

.LBB0_176:
	v_mov_b64_e32 v[2:3], s[76:77]
	s_ashr_i32 s11, s10, 31
	v_cmp_lt_i64_e32 vcc, s[12:13], v[2:3]
	s_lshl_b64 s[12:13], s[10:11], 19
	s_add_u32 s12, s44, s12
	s_addc_u32 s13, s45, s13
	s_and_b64 s[14:15], vcc, exec
	s_cselect_b32 s11, s13, s23
	s_cselect_b32 s51, s12, s22
	s_ashr_i32 s9, s8, 31
	s_lshl_b64 s[14:15], s[8:9], 19
	s_add_u32 s14, s27, s14
	s_addc_u32 s15, s28, s15
	s_and_b64 s[24:25], vcc, exec
	s_cselect_b32 s9, s15, s19
	s_cselect_b32 s52, s14, s18
	s_add_u32 s53, s18, 0x100
	s_addc_u32 s54, s19, 0
	s_add_u32 s18, s22, 0x40080
	v_mov_b32_e32 v2, 0
	s_addc_u32 s19, s23, 0
	s_mov_b32 s55, -2
	v_mov_b32_e32 v3, v2
	v_mov_b32_e32 v4, v2
	v_mov_b32_e32 v5, v2
	v_mov_b32_e32 v6, v2
	v_mov_b32_e32 v7, v2
	v_mov_b32_e32 v8, v2
	v_mov_b32_e32 v9, v2
	v_mov_b32_e32 v10, v2
	v_mov_b32_e32 v11, v2
	v_mov_b32_e32 v12, v2
	v_mov_b32_e32 v13, v2
	v_mov_b32_e32 v14, v2
	v_mov_b32_e32 v15, v2
	v_mov_b32_e32 v16, v2
	v_mov_b32_e32 v17, v2
	v_mov_b32_e32 v26, v2
	v_mov_b32_e32 v27, v2
	v_mov_b32_e32 v28, v2
	v_mov_b32_e32 v29, v2
	v_mov_b32_e32 v30, v2
	v_mov_b32_e32 v31, v2
	v_mov_b32_e32 v32, v2
	v_mov_b32_e32 v33, v2
	v_mov_b32_e32 v42, v2
	v_mov_b32_e32 v43, v2
	v_mov_b32_e32 v44, v2
	v_mov_b32_e32 v45, v2
	v_mov_b32_e32 v46, v2
	v_mov_b32_e32 v47, v2
	v_mov_b32_e32 v48, v2
	v_mov_b32_e32 v49, v2
	v_mov_b32_e32 v18, v2
	v_mov_b32_e32 v19, v2
	v_mov_b32_e32 v20, v2
	v_mov_b32_e32 v21, v2
	v_mov_b32_e32 v22, v2
	v_mov_b32_e32 v23, v2
	v_mov_b32_e32 v24, v2
	v_mov_b32_e32 v25, v2
	v_mov_b32_e32 v34, v2
	v_mov_b32_e32 v35, v2
	v_mov_b32_e32 v36, v2
	v_mov_b32_e32 v37, v2
	v_mov_b32_e32 v38, v2
	v_mov_b32_e32 v39, v2
	v_mov_b32_e32 v40, v2
	v_mov_b32_e32 v41, v2
	v_mov_b32_e32 v50, v2
	v_mov_b32_e32 v51, v2
	v_mov_b32_e32 v52, v2
	v_mov_b32_e32 v53, v2
	v_mov_b32_e32 v54, v2
	v_mov_b32_e32 v55, v2
	v_mov_b32_e32 v56, v2
	v_mov_b32_e32 v57, v2
	v_mov_b32_e32 v58, v2
	v_mov_b32_e32 v59, v2
	v_mov_b32_e32 v60, v2
	v_mov_b32_e32 v61, v2
	v_mov_b32_e32 v62, v2
	v_mov_b32_e32 v63, v2
	v_mov_b32_e32 v64, v2
	v_mov_b32_e32 v65, v2
	v_mov_b32_e32 v66, v2
	v_mov_b32_e32 v67, v2
	v_mov_b32_e32 v68, v2
	v_mov_b32_e32 v69, v2
	v_mov_b32_e32 v70, v2
	v_mov_b32_e32 v71, v2
	v_mov_b32_e32 v72, v2
	v_mov_b32_e32 v73, v2
	v_mov_b32_e32 v74, v2
	v_mov_b32_e32 v75, v2
	v_mov_b32_e32 v76, v2
	v_mov_b32_e32 v77, v2
	v_mov_b32_e32 v78, v2
	v_mov_b32_e32 v79, v2
	v_mov_b32_e32 v80, v2
	v_mov_b32_e32 v81, v2
	v_mov_b32_e32 v90, v2
	v_mov_b32_e32 v91, v2
	v_mov_b32_e32 v92, v2
	v_mov_b32_e32 v93, v2
	v_mov_b32_e32 v94, v2
	v_mov_b32_e32 v95, v2
	v_mov_b32_e32 v96, v2
	v_mov_b32_e32 v97, v2
	v_mov_b32_e32 v106, v2
	v_mov_b32_e32 v107, v2
	v_mov_b32_e32 v108, v2
	v_mov_b32_e32 v109, v2
	v_mov_b32_e32 v110, v2
	v_mov_b32_e32 v111, v2
	v_mov_b32_e32 v112, v2
	v_mov_b32_e32 v113, v2
	v_mov_b32_e32 v82, v2
	v_mov_b32_e32 v83, v2
	v_mov_b32_e32 v84, v2
	v_mov_b32_e32 v85, v2
	v_mov_b32_e32 v86, v2
	v_mov_b32_e32 v87, v2
	v_mov_b32_e32 v88, v2
	v_mov_b32_e32 v89, v2
	v_mov_b32_e32 v98, v2
	v_mov_b32_e32 v99, v2
	v_mov_b32_e32 v100, v2
	v_mov_b32_e32 v101, v2
	v_mov_b32_e32 v102, v2
	v_mov_b32_e32 v103, v2
	v_mov_b32_e32 v104, v2
	v_mov_b32_e32 v105, v2
	v_mov_b32_e32 v114, v2
	v_mov_b32_e32 v115, v2
	v_mov_b32_e32 v116, v2
	v_mov_b32_e32 v117, v2
	v_mov_b32_e32 v118, v2
	v_mov_b32_e32 v119, v2
	v_mov_b32_e32 v120, v2
	v_mov_b32_e32 v121, v2
	v_mov_b32_e32 v122, v2
	v_mov_b32_e32 v123, v2
	v_mov_b32_e32 v124, v2
	v_mov_b32_e32 v125, v2
	v_mov_b32_e32 v126, v2
	v_mov_b32_e32 v127, v2
	v_mov_b32_e32 v128, v2
	v_mov_b32_e32 v129, v2
	.p2align 6

.LBB0_201:
	s_ashr_i32 s27, s26, 31
	v_cmp_lt_i64_e64 s[38:39], s[28:29], 16
	s_lshl_b64 s[28:29], s[26:27], 19
	s_add_u32 s28, s46, s28
	s_addc_u32 s29, s47, s29
	s_and_b64 s[30:31], s[38:39], exec
	s_cselect_b32 s27, s29, s45
	s_cselect_b32 s55, s28, s44
	s_ashr_i32 s25, s24, 31
	s_lshl_b64 s[30:31], s[24:25], 19
	s_add_u32 s30, s12, s30
	s_addc_u32 s31, s13, s31
	s_and_b64 s[38:39], s[38:39], exec
	s_mov_b32 s67, s57
	s_cselect_b32 s25, s31, s35
	s_cselect_b32 s56, s30, s34
	s_add_u32 s57, s34, 0x100
	s_addc_u32 s58, s35, 0
	s_add_u32 s34, s44, 0x40080
	v_mov_b32_e32 v2, 0
	s_addc_u32 s35, s45, 0
	s_mov_b32 s59, -2
	v_mov_b32_e32 v3, v2
	v_mov_b32_e32 v4, v2
	v_mov_b32_e32 v5, v2
	v_mov_b32_e32 v6, v2
	v_mov_b32_e32 v7, v2
	v_mov_b32_e32 v8, v2
	v_mov_b32_e32 v9, v2
	v_mov_b32_e32 v10, v2
	v_mov_b32_e32 v11, v2
	v_mov_b32_e32 v12, v2
	v_mov_b32_e32 v13, v2
	v_mov_b32_e32 v14, v2
	v_mov_b32_e32 v15, v2
	v_mov_b32_e32 v16, v2
	v_mov_b32_e32 v17, v2
	v_mov_b32_e32 v26, v2
	v_mov_b32_e32 v27, v2
	v_mov_b32_e32 v28, v2
	v_mov_b32_e32 v29, v2
	v_mov_b32_e32 v30, v2
	v_mov_b32_e32 v31, v2
	v_mov_b32_e32 v32, v2
	v_mov_b32_e32 v33, v2
	v_mov_b32_e32 v42, v2
	v_mov_b32_e32 v43, v2
	v_mov_b32_e32 v44, v2
	v_mov_b32_e32 v45, v2
	v_mov_b32_e32 v46, v2
	v_mov_b32_e32 v47, v2
	v_mov_b32_e32 v48, v2
	v_mov_b32_e32 v49, v2
	v_mov_b32_e32 v18, v2
	v_mov_b32_e32 v19, v2
	v_mov_b32_e32 v20, v2
	v_mov_b32_e32 v21, v2
	v_mov_b32_e32 v22, v2
	v_mov_b32_e32 v23, v2
	v_mov_b32_e32 v24, v2
	v_mov_b32_e32 v25, v2
	v_mov_b32_e32 v34, v2
	v_mov_b32_e32 v35, v2
	v_mov_b32_e32 v36, v2
	v_mov_b32_e32 v37, v2
	v_mov_b32_e32 v38, v2
	v_mov_b32_e32 v39, v2
	v_mov_b32_e32 v40, v2
	v_mov_b32_e32 v41, v2
	v_mov_b32_e32 v50, v2
	v_mov_b32_e32 v51, v2
	v_mov_b32_e32 v52, v2
	v_mov_b32_e32 v53, v2
	v_mov_b32_e32 v54, v2
	v_mov_b32_e32 v55, v2
	v_mov_b32_e32 v56, v2
	v_mov_b32_e32 v57, v2
	v_mov_b32_e32 v58, v2
	v_mov_b32_e32 v59, v2
	v_mov_b32_e32 v60, v2
	v_mov_b32_e32 v61, v2
	v_mov_b32_e32 v62, v2
	v_mov_b32_e32 v63, v2
	v_mov_b32_e32 v64, v2
	v_mov_b32_e32 v65, v2
	v_mov_b32_e32 v66, v2
	v_mov_b32_e32 v67, v2
	v_mov_b32_e32 v68, v2
	v_mov_b32_e32 v69, v2
	v_mov_b32_e32 v70, v2
	v_mov_b32_e32 v71, v2
	v_mov_b32_e32 v72, v2
	v_mov_b32_e32 v73, v2
	v_mov_b32_e32 v74, v2
	v_mov_b32_e32 v75, v2
	v_mov_b32_e32 v76, v2
	v_mov_b32_e32 v77, v2
	v_mov_b32_e32 v78, v2
	v_mov_b32_e32 v79, v2
	v_mov_b32_e32 v80, v2
	v_mov_b32_e32 v81, v2
	v_mov_b32_e32 v90, v2
	v_mov_b32_e32 v91, v2
	v_mov_b32_e32 v92, v2
	v_mov_b32_e32 v93, v2
	v_mov_b32_e32 v94, v2
	v_mov_b32_e32 v95, v2
	v_mov_b32_e32 v96, v2
	v_mov_b32_e32 v97, v2
	v_mov_b32_e32 v106, v2
	v_mov_b32_e32 v107, v2
	v_mov_b32_e32 v108, v2
	v_mov_b32_e32 v109, v2
	v_mov_b32_e32 v110, v2
	v_mov_b32_e32 v111, v2
	v_mov_b32_e32 v112, v2
	v_mov_b32_e32 v113, v2
	v_mov_b32_e32 v82, v2
	v_mov_b32_e32 v83, v2
	v_mov_b32_e32 v84, v2
	v_mov_b32_e32 v85, v2
	v_mov_b32_e32 v86, v2
	v_mov_b32_e32 v87, v2
	v_mov_b32_e32 v88, v2
	v_mov_b32_e32 v89, v2
	v_mov_b32_e32 v98, v2
	v_mov_b32_e32 v99, v2
	v_mov_b32_e32 v100, v2
	v_mov_b32_e32 v101, v2
	v_mov_b32_e32 v102, v2
	v_mov_b32_e32 v103, v2
	v_mov_b32_e32 v104, v2
	v_mov_b32_e32 v105, v2
	v_mov_b32_e32 v114, v2
	v_mov_b32_e32 v115, v2
	v_mov_b32_e32 v116, v2
	v_mov_b32_e32 v117, v2
	v_mov_b32_e32 v118, v2
	v_mov_b32_e32 v119, v2
	v_mov_b32_e32 v120, v2
	v_mov_b32_e32 v121, v2
	v_mov_b32_e32 v122, v2
	v_mov_b32_e32 v123, v2
	v_mov_b32_e32 v124, v2
	v_mov_b32_e32 v125, v2
	v_mov_b32_e32 v126, v2
	v_mov_b32_e32 v127, v2
	v_mov_b32_e32 v128, v2
	v_mov_b32_e32 v129, v2
	.p2align 6

.LBB0_252:
	s_add_u32 s40, s22, 0x100
	v_mov_b32_e32 v2, 0
	s_addc_u32 s41, s23, 0
	s_mov_b32 s48, -2
	v_mov_b32_e32 v3, v2
	v_mov_b32_e32 v4, v2
	v_mov_b32_e32 v5, v2
	v_mov_b32_e32 v6, v2
	v_mov_b32_e32 v7, v2
	v_mov_b32_e32 v8, v2
	v_mov_b32_e32 v9, v2
	v_mov_b32_e32 v10, v2
	v_mov_b32_e32 v11, v2
	v_mov_b32_e32 v12, v2
	v_mov_b32_e32 v13, v2
	v_mov_b32_e32 v14, v2
	v_mov_b32_e32 v15, v2
	v_mov_b32_e32 v16, v2
	v_mov_b32_e32 v17, v2
	v_mov_b32_e32 v26, v2
	v_mov_b32_e32 v27, v2
	v_mov_b32_e32 v28, v2
	v_mov_b32_e32 v29, v2
	v_mov_b32_e32 v30, v2
	v_mov_b32_e32 v31, v2
	v_mov_b32_e32 v32, v2
	v_mov_b32_e32 v33, v2
	v_mov_b32_e32 v42, v2
	v_mov_b32_e32 v43, v2
	v_mov_b32_e32 v44, v2
	v_mov_b32_e32 v45, v2
	v_mov_b32_e32 v46, v2
	v_mov_b32_e32 v47, v2
	v_mov_b32_e32 v48, v2
	v_mov_b32_e32 v49, v2
	v_mov_b32_e32 v18, v2
	v_mov_b32_e32 v19, v2
	v_mov_b32_e32 v20, v2
	v_mov_b32_e32 v21, v2
	v_mov_b32_e32 v22, v2
	v_mov_b32_e32 v23, v2
	v_mov_b32_e32 v24, v2
	v_mov_b32_e32 v25, v2
	v_mov_b32_e32 v34, v2
	v_mov_b32_e32 v35, v2
	v_mov_b32_e32 v36, v2
	v_mov_b32_e32 v37, v2
	v_mov_b32_e32 v38, v2
	v_mov_b32_e32 v39, v2
	v_mov_b32_e32 v40, v2
	v_mov_b32_e32 v41, v2
	v_mov_b32_e32 v50, v2
	v_mov_b32_e32 v51, v2
	v_mov_b32_e32 v52, v2
	v_mov_b32_e32 v53, v2
	v_mov_b32_e32 v54, v2
	v_mov_b32_e32 v55, v2
	v_mov_b32_e32 v56, v2
	v_mov_b32_e32 v57, v2
	v_mov_b32_e32 v58, v2
	v_mov_b32_e32 v59, v2
	v_mov_b32_e32 v60, v2
	v_mov_b32_e32 v61, v2
	v_mov_b32_e32 v62, v2
	v_mov_b32_e32 v63, v2
	v_mov_b32_e32 v64, v2
	v_mov_b32_e32 v65, v2
	v_mov_b32_e32 v66, v2
	v_mov_b32_e32 v67, v2
	v_mov_b32_e32 v68, v2
	v_mov_b32_e32 v69, v2
	v_mov_b32_e32 v70, v2
	v_mov_b32_e32 v71, v2
	v_mov_b32_e32 v72, v2
	v_mov_b32_e32 v73, v2
	v_mov_b32_e32 v74, v2
	v_mov_b32_e32 v75, v2
	v_mov_b32_e32 v76, v2
	v_mov_b32_e32 v77, v2
	v_mov_b32_e32 v78, v2
	v_mov_b32_e32 v79, v2
	v_mov_b32_e32 v80, v2
	v_mov_b32_e32 v81, v2
	v_mov_b32_e32 v90, v2
	v_mov_b32_e32 v91, v2
	v_mov_b32_e32 v92, v2
	v_mov_b32_e32 v93, v2
	v_mov_b32_e32 v94, v2
	v_mov_b32_e32 v95, v2
	v_mov_b32_e32 v96, v2
	v_mov_b32_e32 v97, v2
	v_mov_b32_e32 v106, v2
	v_mov_b32_e32 v107, v2
	v_mov_b32_e32 v108, v2
	v_mov_b32_e32 v109, v2
	v_mov_b32_e32 v110, v2
	v_mov_b32_e32 v111, v2
	v_mov_b32_e32 v112, v2
	v_mov_b32_e32 v113, v2
	v_mov_b32_e32 v82, v2
	v_mov_b32_e32 v83, v2
	v_mov_b32_e32 v84, v2
	v_mov_b32_e32 v85, v2
	v_mov_b32_e32 v86, v2
	v_mov_b32_e32 v87, v2
	v_mov_b32_e32 v88, v2
	v_mov_b32_e32 v89, v2
	v_mov_b32_e32 v98, v2
	v_mov_b32_e32 v99, v2
	v_mov_b32_e32 v100, v2
	v_mov_b32_e32 v101, v2
	v_mov_b32_e32 v102, v2
	v_mov_b32_e32 v103, v2
	v_mov_b32_e32 v104, v2
	v_mov_b32_e32 v105, v2
	v_mov_b32_e32 v114, v2
	v_mov_b32_e32 v115, v2
	v_mov_b32_e32 v116, v2
	v_mov_b32_e32 v117, v2
	v_mov_b32_e32 v118, v2
	v_mov_b32_e32 v119, v2
	v_mov_b32_e32 v120, v2
	v_mov_b32_e32 v121, v2
	v_mov_b32_e32 v122, v2
	v_mov_b32_e32 v123, v2
	v_mov_b32_e32 v124, v2
	v_mov_b32_e32 v125, v2
	v_mov_b32_e32 v126, v2
	v_mov_b32_e32 v127, v2
	v_mov_b32_e32 v128, v2
	v_mov_b32_e32 v129, v2
	.p2align 6

.LBB0_285:
	s_ashr_i32 s11, s10, 31
	v_cmp_lt_i64_e32 vcc, s[12:13], v[150:151]
	s_lshl_b64 s[12:13], s[10:11], 19
	s_add_u32 s12, s44, s12
	s_addc_u32 s13, s45, s13
	s_and_b64 s[14:15], vcc, exec
	s_cselect_b32 s11, s13, s23
	s_cselect_b32 s48, s12, s22
	s_ashr_i32 s9, s8, 31
	s_lshl_b64 s[14:15], s[8:9], 19
	s_add_u32 s14, s27, s14
	s_addc_u32 s15, s28, s15
	s_and_b64 s[24:25], vcc, exec
	s_cselect_b32 s9, s15, s19
	s_cselect_b32 s49, s14, s18
	s_add_u32 s50, s18, 0x100
	s_addc_u32 s51, s19, 0
	s_add_u32 s18, s22, 0x40080
	v_mov_b32_e32 v2, 0
	s_addc_u32 s19, s23, 0
	s_mov_b32 s52, -2
	v_mov_b32_e32 v3, v2
	v_mov_b32_e32 v4, v2
	v_mov_b32_e32 v5, v2
	v_mov_b32_e32 v6, v2
	v_mov_b32_e32 v7, v2
	v_mov_b32_e32 v8, v2
	v_mov_b32_e32 v9, v2
	v_mov_b32_e32 v10, v2
	v_mov_b32_e32 v11, v2
	v_mov_b32_e32 v12, v2
	v_mov_b32_e32 v13, v2
	v_mov_b32_e32 v14, v2
	v_mov_b32_e32 v15, v2
	v_mov_b32_e32 v16, v2
	v_mov_b32_e32 v17, v2
	v_mov_b32_e32 v26, v2
	v_mov_b32_e32 v27, v2
	v_mov_b32_e32 v28, v2
	v_mov_b32_e32 v29, v2
	v_mov_b32_e32 v30, v2
	v_mov_b32_e32 v31, v2
	v_mov_b32_e32 v32, v2
	v_mov_b32_e32 v33, v2
	v_mov_b32_e32 v42, v2
	v_mov_b32_e32 v43, v2
	v_mov_b32_e32 v44, v2
	v_mov_b32_e32 v45, v2
	v_mov_b32_e32 v46, v2
	v_mov_b32_e32 v47, v2
	v_mov_b32_e32 v48, v2
	v_mov_b32_e32 v49, v2
	v_mov_b32_e32 v18, v2
	v_mov_b32_e32 v19, v2
	v_mov_b32_e32 v20, v2
	v_mov_b32_e32 v21, v2
	v_mov_b32_e32 v22, v2
	v_mov_b32_e32 v23, v2
	v_mov_b32_e32 v24, v2
	v_mov_b32_e32 v25, v2
	v_mov_b32_e32 v34, v2
	v_mov_b32_e32 v35, v2
	v_mov_b32_e32 v36, v2
	v_mov_b32_e32 v37, v2
	v_mov_b32_e32 v38, v2
	v_mov_b32_e32 v39, v2
	v_mov_b32_e32 v40, v2
	v_mov_b32_e32 v41, v2
	v_mov_b32_e32 v50, v2
	v_mov_b32_e32 v51, v2
	v_mov_b32_e32 v52, v2
	v_mov_b32_e32 v53, v2
	v_mov_b32_e32 v54, v2
	v_mov_b32_e32 v55, v2
	v_mov_b32_e32 v56, v2
	v_mov_b32_e32 v57, v2
	v_mov_b32_e32 v58, v2
	v_mov_b32_e32 v59, v2
	v_mov_b32_e32 v60, v2
	v_mov_b32_e32 v61, v2
	v_mov_b32_e32 v62, v2
	v_mov_b32_e32 v63, v2
	v_mov_b32_e32 v64, v2
	v_mov_b32_e32 v65, v2
	v_mov_b32_e32 v66, v2
	v_mov_b32_e32 v67, v2
	v_mov_b32_e32 v68, v2
	v_mov_b32_e32 v69, v2
	v_mov_b32_e32 v70, v2
	v_mov_b32_e32 v71, v2
	v_mov_b32_e32 v72, v2
	v_mov_b32_e32 v73, v2
	v_mov_b32_e32 v74, v2
	v_mov_b32_e32 v75, v2
	v_mov_b32_e32 v76, v2
	v_mov_b32_e32 v77, v2
	v_mov_b32_e32 v78, v2
	v_mov_b32_e32 v79, v2
	v_mov_b32_e32 v80, v2
	v_mov_b32_e32 v81, v2
	v_mov_b32_e32 v90, v2
	v_mov_b32_e32 v91, v2
	v_mov_b32_e32 v92, v2
	v_mov_b32_e32 v93, v2
	v_mov_b32_e32 v94, v2
	v_mov_b32_e32 v95, v2
	v_mov_b32_e32 v96, v2
	v_mov_b32_e32 v97, v2
	v_mov_b32_e32 v106, v2
	v_mov_b32_e32 v107, v2
	v_mov_b32_e32 v108, v2
	v_mov_b32_e32 v109, v2
	v_mov_b32_e32 v110, v2
	v_mov_b32_e32 v111, v2
	v_mov_b32_e32 v112, v2
	v_mov_b32_e32 v113, v2
	v_mov_b32_e32 v82, v2
	v_mov_b32_e32 v83, v2
	v_mov_b32_e32 v84, v2
	v_mov_b32_e32 v85, v2
	v_mov_b32_e32 v86, v2
	v_mov_b32_e32 v87, v2
	v_mov_b32_e32 v88, v2
	v_mov_b32_e32 v89, v2
	v_mov_b32_e32 v98, v2
	v_mov_b32_e32 v99, v2
	v_mov_b32_e32 v100, v2
	v_mov_b32_e32 v101, v2
	v_mov_b32_e32 v102, v2
	v_mov_b32_e32 v103, v2
	v_mov_b32_e32 v104, v2
	v_mov_b32_e32 v105, v2
	v_mov_b32_e32 v114, v2
	v_mov_b32_e32 v115, v2
	v_mov_b32_e32 v116, v2
	v_mov_b32_e32 v117, v2
	v_mov_b32_e32 v118, v2
	v_mov_b32_e32 v119, v2
	v_mov_b32_e32 v120, v2
	v_mov_b32_e32 v121, v2
	v_mov_b32_e32 v122, v2
	v_mov_b32_e32 v123, v2
	v_mov_b32_e32 v124, v2
	v_mov_b32_e32 v125, v2
	v_mov_b32_e32 v126, v2
	v_mov_b32_e32 v127, v2
	v_mov_b32_e32 v128, v2
	v_mov_b32_e32 v129, v2
	.p2align 6

.LBB0_444:
	s_or_b64 exec, exec, s[14:15]
	s_setprio 0
	v_add_u32_e32 v0, -1, v0
	v_mov_b32_e32 v84, v83
	s_andn2_b64 exec, exec, s[10:11]
	s_cbranch_execz .LBB0_474
	.p2align 6

.Lwoff_ml_a:
	.p2align 6

.LBB0_671:
	s_ashr_i32 s11, s10, 31
	v_cmp_lt_i64_e32 vcc, s[12:13], v[156:157]
	s_lshl_b64 s[12:13], s[10:11], 19
	s_add_u32 s12, s44, s12
	s_addc_u32 s13, s45, s13
	s_and_b64 s[14:15], vcc, exec
	s_cselect_b32 s11, s13, s23
	s_cselect_b32 s48, s12, s22
	s_ashr_i32 s9, s8, 31
	s_lshl_b64 s[14:15], s[8:9], 19
	s_add_u32 s14, s26, s14
	s_addc_u32 s15, s27, s15
	s_and_b64 s[24:25], vcc, exec
	s_cselect_b32 s9, s15, s19
	s_cselect_b32 s49, s14, s18
	s_add_u32 s50, s18, 0x100
	s_addc_u32 s51, s19, 0
	s_add_u32 s18, s22, 0x40080
	v_mov_b32_e32 v2, 0
	s_addc_u32 s19, s23, 0
	s_mov_b32 s52, -2
	v_mov_b32_e32 v3, v2
	v_mov_b32_e32 v4, v2
	v_mov_b32_e32 v5, v2
	v_mov_b32_e32 v6, v2
	v_mov_b32_e32 v7, v2
	v_mov_b32_e32 v8, v2
	v_mov_b32_e32 v9, v2
	v_mov_b32_e32 v10, v2
	v_mov_b32_e32 v11, v2
	v_mov_b32_e32 v12, v2
	v_mov_b32_e32 v13, v2
	v_mov_b32_e32 v14, v2
	v_mov_b32_e32 v15, v2
	v_mov_b32_e32 v16, v2
	v_mov_b32_e32 v17, v2
	v_mov_b32_e32 v26, v2
	v_mov_b32_e32 v27, v2
	v_mov_b32_e32 v28, v2
	v_mov_b32_e32 v29, v2
	v_mov_b32_e32 v30, v2
	v_mov_b32_e32 v31, v2
	v_mov_b32_e32 v32, v2
	v_mov_b32_e32 v33, v2
	v_mov_b32_e32 v42, v2
	v_mov_b32_e32 v43, v2
	v_mov_b32_e32 v44, v2
	v_mov_b32_e32 v45, v2
	v_mov_b32_e32 v46, v2
	v_mov_b32_e32 v47, v2
	v_mov_b32_e32 v48, v2
	v_mov_b32_e32 v49, v2
	v_mov_b32_e32 v18, v2
	v_mov_b32_e32 v19, v2
	v_mov_b32_e32 v20, v2
	v_mov_b32_e32 v21, v2
	v_mov_b32_e32 v22, v2
	v_mov_b32_e32 v23, v2
	v_mov_b32_e32 v24, v2
	v_mov_b32_e32 v25, v2
	v_mov_b32_e32 v34, v2
	v_mov_b32_e32 v35, v2
	v_mov_b32_e32 v36, v2
	v_mov_b32_e32 v37, v2
	v_mov_b32_e32 v38, v2
	v_mov_b32_e32 v39, v2
	v_mov_b32_e32 v40, v2
	v_mov_b32_e32 v41, v2
	v_mov_b32_e32 v50, v2
	v_mov_b32_e32 v51, v2
	v_mov_b32_e32 v52, v2
	v_mov_b32_e32 v53, v2
	v_mov_b32_e32 v54, v2
	v_mov_b32_e32 v55, v2
	v_mov_b32_e32 v56, v2
	v_mov_b32_e32 v57, v2
	v_mov_b32_e32 v58, v2
	v_mov_b32_e32 v59, v2
	v_mov_b32_e32 v60, v2
	v_mov_b32_e32 v61, v2
	v_mov_b32_e32 v62, v2
	v_mov_b32_e32 v63, v2
	v_mov_b32_e32 v64, v2
	v_mov_b32_e32 v65, v2
	v_mov_b32_e32 v66, v2
	v_mov_b32_e32 v67, v2
	v_mov_b32_e32 v68, v2
	v_mov_b32_e32 v69, v2
	v_mov_b32_e32 v70, v2
	v_mov_b32_e32 v71, v2
	v_mov_b32_e32 v72, v2
	v_mov_b32_e32 v73, v2
	v_mov_b32_e32 v74, v2
	v_mov_b32_e32 v75, v2
	v_mov_b32_e32 v76, v2
	v_mov_b32_e32 v77, v2
	v_mov_b32_e32 v78, v2
	v_mov_b32_e32 v79, v2
	v_mov_b32_e32 v80, v2
	v_mov_b32_e32 v81, v2
	v_mov_b32_e32 v90, v2
	v_mov_b32_e32 v91, v2
	v_mov_b32_e32 v92, v2
	v_mov_b32_e32 v93, v2
	v_mov_b32_e32 v94, v2
	v_mov_b32_e32 v95, v2
	v_mov_b32_e32 v96, v2
	v_mov_b32_e32 v97, v2
	v_mov_b32_e32 v106, v2
	v_mov_b32_e32 v107, v2
	v_mov_b32_e32 v108, v2
	v_mov_b32_e32 v109, v2
	v_mov_b32_e32 v110, v2
	v_mov_b32_e32 v111, v2
	v_mov_b32_e32 v112, v2
	v_mov_b32_e32 v113, v2
	v_mov_b32_e32 v82, v2
	v_mov_b32_e32 v83, v2
	v_mov_b32_e32 v84, v2
	v_mov_b32_e32 v85, v2
	v_mov_b32_e32 v86, v2
	v_mov_b32_e32 v87, v2
	v_mov_b32_e32 v88, v2
	v_mov_b32_e32 v89, v2
	v_mov_b32_e32 v98, v2
	v_mov_b32_e32 v99, v2
	v_mov_b32_e32 v100, v2
	v_mov_b32_e32 v101, v2
	v_mov_b32_e32 v102, v2
	v_mov_b32_e32 v103, v2
	v_mov_b32_e32 v104, v2
	v_mov_b32_e32 v105, v2
	v_mov_b32_e32 v114, v2
	v_mov_b32_e32 v115, v2
	v_mov_b32_e32 v116, v2
	v_mov_b32_e32 v117, v2
	v_mov_b32_e32 v118, v2
	v_mov_b32_e32 v119, v2
	v_mov_b32_e32 v120, v2
	v_mov_b32_e32 v121, v2
	v_mov_b32_e32 v122, v2
	v_mov_b32_e32 v123, v2
	v_mov_b32_e32 v124, v2
	v_mov_b32_e32 v125, v2
	v_mov_b32_e32 v126, v2
	v_mov_b32_e32 v127, v2
	v_mov_b32_e32 v128, v2
	v_mov_b32_e32 v129, v2
	.p2align 6
